# five weight transposes and the gate-weight folding moved from phase 0 to the 240 workgroups that idle during the second A-out GEMM round (same code re-entered with a mode flag)
# speedup vs baseline: 1.0808x; 1.0225x over previous
_Z14fwd_megakernel6Params:
	s_mov_b64 s[96:97], s[0:1]
	s_mov_b32 s98, 0
	v_and_b32_e32 v1, 0x3ff, v0
	s_add_u32 s20, s96, 0xc8
	s_load_dword s52, s[0:1], 0xc8
	v_readfirstlane_b32 s0, v1
	v_mbcnt_lo_u32_b32 v2, -1, 0
	s_addc_u32 s21, s97, 0
	s_andn2_b32 s0, s0, 63
	v_mbcnt_hi_u32_b32 v200, -1, v2
	v_add_u32_e32 v201, s0, v200
	v_mov_b32_e32 v2, v201
	s_nop 0
	v_cmp_eq_u32_e32 vcc, 0, v2
	s_and_saveexec_b64 s[4:5], vcc
	s_cbranch_execz .LBB0_2
	s_add_i32 s0, 0, 0x25fc0
	v_mov_b32_e32 v2, 0
	v_mov_b32_e32 v3, s0
	s_add_i32 s0, 0, 0x25fc4
	ds_write_b32 v3, v2
	v_mov_b32_e32 v3, s0
	ds_write_b32 v3, v2

.Lp0_entry:
	s_mov_b64 s[0:1], s[96:97]
	s_load_dwordx4 s[16:19], s[0:1], 0x0
	s_load_dwordx2 s[24:25], s[0:1], 0x38
	s_load_dwordx2 s[30:31], s[0:1], 0x48
	s_load_dwordx4 s[4:7], s[0:1], 0x58
	s_load_dwordx8 s[8:15], s[0:1], 0x78
	s_load_dwordx2 s[26:27], s[0:1], 0xb0
	s_load_dwordx2 s[22:23], s[0:1], 0xc0
	v_mov_b32_e32 v2, v201
	s_mov_b32 s3, 0
	s_lshl_b64 s[0:1], s[2:3], 9
	v_ashrrev_i32_e32 v3, 31, v2
	v_lshl_add_u64 v[44:45], s[0:1], 0, v[2:3]
	s_cmp_eq_u32 s98, 1
	s_cbranch_scc1 .Lp0_skipzero
	s_mov_b64 s[0:1], 0x4c800
	v_cmp_gt_u64_e32 vcc, s[0:1], v[44:45]
	s_and_saveexec_b64 s[28:29], vcc
	s_cbranch_execz .LBB0_7
	s_ashr_i32 s53, s52, 31
	s_lshl_b64 s[34:35], s[52:53], 9
	s_lshl_b64 s[0:1], s[2:3], 11
	s_waitcnt lgkmcnt(0)
	s_add_u32 s0, s22, s0
	s_addc_u32 s1, s23, s1
	v_lshl_add_u64 v[4:5], v[2:3], 2, s[0:1]
	s_mov_b64 s[0:1], 0x3a20000
	v_lshl_add_u64 v[4:5], v[4:5], 0, s[0:1]
	s_lshl_b64 s[36:37], s[52:53], 11
	s_mov_b64 s[38:39], 0
	v_mov_b32_e32 v3, 0
	s_mov_b64 s[40:41], 0x4c7ff
	v_mov_b64_e32 v[6:7], v[44:45]

.Lp0_skipzero:
	v_ashrrev_i32_e32 v8, 6, v2
	s_lshl_b32 s0, s2, 3
	v_and_b32_e32 v47, 63, v2
	v_writelane_b32 v255, s0, 0
	v_add_u32_e32 v51, s0, v8
	s_movk_i32 s0, 0x3800
	s_lshl_b32 s33, s52, 3
	s_cmp_eq_u32 s98, 1
	s_cselect_b32 s0, s0, 0x1400
	s_cselect_b32 s33, 0x780, s33
	s_cselect_b32 s60, 0x1380, 0
	v_add_u32_e32 v51, s60, v51
	v_cmp_gt_i32_e32 vcc, s0, v51
	v_lshlrev_b32_e32 v18, 3, v47
	s_and_saveexec_b64 s[28:29], vcc
	s_cbranch_execz .LBB0_34
	v_lshrrev_b32_e32 v19, 5, v47
	v_and_b32_e32 v26, 31, v2
	s_movk_i32 s0, 0x84
	v_mov_b32_e32 v2, 0x630
	v_mad_u32_u24 v35, v19, s0, v2
	v_mov_b32_e32 v2, 0xc60
	v_mad_u32_u24 v42, v19, s0, v2
	v_mov_b32_e32 v2, 0x1290
	v_mad_u32_u24 v53, v19, s0, v2
	v_mov_b32_e32 v2, 0x18c0
	v_mad_u32_u24 v60, v19, s0, v2
	v_and_b32_e32 v2, 56, v18
	v_lshrrev_b32_e32 v68, 3, v47
	v_mul_u32_u24_e32 v9, 0x84, v2
	v_lshlrev_b32_e32 v2, 1, v2
	v_mov_b32_e32 v3, 0
	v_lshl_add_u32 v7, v8, 14, 0
	s_waitcnt lgkmcnt(0)
	v_lshl_add_u64 v[4:5], s[22:23], 0, v[2:3]
	v_lshlrev_b32_e32 v2, 2, v68
	v_add3_u32 v69, v7, v9, v2
	v_lshlrev_b32_e32 v2, 5, v8
	v_lshl_add_u32 v74, s2, 8, v2
	v_lshlrev_b32_e32 v2, 7, v8
	v_lshlrev_b32_e32 v6, 2, v26
	v_lshl_add_u32 v75, s2, 10, v2
	v_lshlrev_b32_e32 v2, 6, v8
	v_add_u32_e32 v27, v7, v6
	v_mov_b32_e32 v7, v3
	v_lshl_add_u32 v76, s2, 9, v2
	v_lshlrev_b32_e32 v2, 1, v8
	s_mov_b64 s[36:37], 0x3600000
	s_mov_b64 s[38:39], 0x2d00000
	s_mov_b64 s[40:41], 0x2500000
	s_mov_b64 s[42:43], 0x1c00000
	s_mov_b64 s[44:45], 0x1400000
	s_mov_b64 s[46:47], 0x1000000
	v_lshl_add_u64 v[6:7], s[30:31], 0, v[6:7]
	s_add_u32 s30, s24, 0x1000
	v_lshl_add_u32 v2, s2, 4, v2
	v_mul_u32_u24_e32 v28, 0x84, v19
	v_or_b32_e32 v29, 2, v19
	v_or_b32_e32 v30, 4, v19
	v_or_b32_e32 v31, 6, v19
	v_or_b32_e32 v32, 8, v19
	v_or_b32_e32 v33, 10, v19
	v_or_b32_e32 v34, 12, v19
	v_or_b32_e32 v36, 14, v19
	v_or_b32_e32 v37, 16, v19
	v_or_b32_e32 v38, 18, v19
	v_or_b32_e32 v39, 20, v19
	v_or_b32_e32 v40, 22, v19
	v_or_b32_e32 v41, 24, v19
	v_or_b32_e32 v43, 26, v19
	v_or_b32_e32 v46, 28, v19
	v_or_b32_e32 v48, 30, v19
	v_or_b32_e32 v49, 32, v19
	v_or_b32_e32 v50, 34, v19
	v_or_b32_e32 v52, 36, v19
	v_or_b32_e32 v54, 38, v19
	v_or_b32_e32 v55, 40, v19
	v_or_b32_e32 v56, 42, v19
	v_or_b32_e32 v57, 44, v19
	v_or_b32_e32 v58, 46, v19
	v_or_b32_e32 v59, 48, v19
	v_or_b32_e32 v61, 50, v19
	v_or_b32_e32 v62, 52, v19
	v_or_b32_e32 v63, 54, v19
	v_or_b32_e32 v64, 56, v19
	v_or_b32_e32 v65, 58, v19
	v_or_b32_e32 v66, 60, v19
	v_or_b32_e32 v67, 62, v19
	v_or_b32_e32 v70, 8, v68
	v_or_b32_e32 v71, 16, v68
	v_or_b32_e32 v72, 24, v68
	v_bitop3_b32 v73, v68, 15, 24 bitop3:0xc8
	s_addc_u32 s31, s25, 0
	s_lshl_b32 s0, s33, 5
	s_lshl_b32 s1, s33, 7
	s_lshl_b32 s3, s33, 6
	v_add_u32_e32 v77, 0x19800, v2
	s_lshl_b32 s48, s33, 1
	s_mov_b64 s[34:35], 0
	s_movk_i32 s49, 0xfff
	s_movk_i32 s50, 0x13ff
	s_movk_i32 s51, 0x1bff
	s_movk_i32 s53, 0x23ff
	s_movk_i32 s54, 0x2bff
	s_movk_i32 s55, 0x33ff
	s_movk_i32 s56, 0x7fff
	s_mov_b32 s57, 0xffff0000
	s_movk_i32 s58, 0x37ff
	v_mov_b32_e32 v78, v51
	v_lshl_add_u64 v[8:9], v[4:5], 0, s[36:37]
	v_lshl_add_u64 v[10:11], v[4:5], 0, s[38:39]
	v_lshl_add_u64 v[12:13], v[4:5], 0, s[40:41]
	v_lshl_add_u64 v[14:15], v[4:5], 0, s[42:43]
	v_lshl_add_u64 v[16:17], v[4:5], 0, s[44:45]
	v_lshl_add_u64 v[20:21], v[4:5], 0, s[46:47]
	s_cmp_eq_u32 s98, 1
	s_cselect_b32 s58, s58, 0x13ff
	s_cselect_b32 s60, 0x27000, 0
	s_cselect_b32 s61, 0x9c000, 0
	v_add_u32_e32 v74, s60, v74
	v_add_u32_e32 v75, s61, v75
	s_cselect_b32 s60, 0x4e000, 0
	s_cselect_b32 s61, 0x2700, 0
	v_add_u32_e32 v76, s60, v76
	v_add_u32_e32 v77, s61, v77
	s_branch .LBB0_10

.LBB0_34:
	s_or_b64 exec, exec, s[28:29]
	s_cmp_eq_u32 s98, 1
	s_cselect_b32 s0, 0, 0x4400
	v_cmp_gt_i32_e32 vcc, s0, v51
	v_lshlrev_b32_e32 v46, 2, v47
	v_and_b32_e32 v208, 64, v200
	v_xor_b32_e32 v207, 1, v200
	v_xor_b32_e32 v206, 2, v200
	v_xor_b32_e32 v205, 4, v200
	v_xor_b32_e32 v204, 8, v200
	v_xor_b32_e32 v203, 16, v200
	v_xor_b32_e32 v202, 32, v200
	s_waitcnt lgkmcnt(0)
	s_and_saveexec_b64 s[6:7], vcc
	s_cbranch_execz .LBB0_41
	v_mov_b32_e32 v49, 0
	v_lshlrev_b32_e32 v48, 4, v47
	v_lshl_add_u64 v[20:21], s[24:25], 0, v[48:49]
	flat_load_dwordx4 v[2:5], v[20:21]
	flat_load_dwordx4 v[6:9], v[20:21] offset:1024
	flat_load_dwordx4 v[10:13], v[20:21] offset:2048
	flat_load_dwordx4 v[14:17], v[20:21] offset:3072
	v_add_u32_e32 v19, 64, v208
	v_cmp_lt_i32_e32 vcc, v207, v19
	s_mov_b64 s[4:5], 0x3b52000
	s_mov_b64 s[24:25], 0
	v_cndmask_b32_e32 v20, v200, v207, vcc
	v_cmp_lt_i32_e32 vcc, v206, v19
	s_movk_i32 s1, 0x3fff
	s_movk_i32 s3, 0x4000
	v_cndmask_b32_e32 v21, v200, v206, vcc
	v_cmp_lt_i32_e32 vcc, v205, v19
	s_mov_b32 s26, 0x3a800000
	s_mov_b32 s27, 0x800000
	v_cndmask_b32_e32 v22, v200, v205, vcc
	v_cmp_lt_i32_e32 vcc, v204, v19
	s_movk_i32 s28, 0x7fff
	s_movk_i32 s29, 0x43ff
	v_cndmask_b32_e32 v23, v200, v204, vcc
	v_cmp_lt_i32_e32 vcc, v203, v19
	v_mov_b32_e32 v50, 0x358637bd
	v_mov_b32_e32 v60, 1
	v_cndmask_b32_e32 v24, v200, v203, vcc
	v_cmp_lt_i32_e32 vcc, v202, v19
	v_mov_b32_e32 v19, v49
	v_lshl_add_u64 v[18:19], s[22:23], 0, v[18:19]
	v_cndmask_b32_e32 v25, v200, v202, vcc
	v_lshlrev_b32_e32 v48, 2, v46
	v_lshlrev_b32_e32 v61, 2, v20
	v_lshlrev_b32_e32 v62, 2, v21
	v_lshlrev_b32_e32 v63, 2, v22
	v_lshlrev_b32_e32 v64, 2, v23
	v_lshlrev_b32_e32 v65, 2, v24
	v_lshlrev_b32_e32 v66, 2, v25
	v_lshl_add_u64 v[52:53], v[18:19], 0, s[4:5]
	v_mov_b32_e32 v56, v51
	s_waitcnt vmcnt(0) lgkmcnt(0)
	v_mov_b32_e32 v54, v3
	v_mov_b32_e32 v55, v5
	v_mov_b32_e32 v3, v4
	v_mov_b32_e32 v4, v7
	v_mov_b32_e32 v5, v9
	v_mov_b32_e32 v7, v8
	v_mov_b32_e32 v8, v11
	v_mov_b32_e32 v9, v13
	v_mov_b32_e32 v11, v12
	v_mov_b32_e32 v12, v15
	v_mov_b32_e32 v13, v17
	v_mov_b32_e32 v15, v16
	s_branch .LBB0_37

.LBB0_41:
	s_or_b64 exec, exec, s[6:7]
	s_cmp_eq_u32 s98, 1
	s_cselect_b32 s0, 0x1000, 0
	s_cselect_b32 s60, 0x1400, 0
	v_subrev_u32_e32 v51, s60, v51
	v_cmp_gt_i32_e32 vcc, s0, v51
	s_and_saveexec_b64 s[16:17], vcc
	s_cbranch_execz .LBB0_51
	v_add_u32_e32 v2, 64, v208
	v_cmp_lt_i32_e32 vcc, v207, v2
	v_cmp_eq_u32_e64 s[4:5], 0, v47
	s_movk_i32 s1, 0x800
	v_cndmask_b32_e32 v3, v200, v207, vcc
	v_cmp_lt_i32_e32 vcc, v206, v2
	v_lshlrev_b32_e32 v24, 2, v3
	s_movk_i32 s3, 0x7ff
	v_cndmask_b32_e32 v3, v200, v206, vcc
	v_cmp_lt_i32_e32 vcc, v205, v2
	v_lshlrev_b32_e32 v25, 2, v3
	v_mov_b32_e32 v30, 0x20000
	v_cndmask_b32_e32 v3, v200, v205, vcc
	v_cmp_lt_i32_e32 vcc, v204, v2
	v_lshlrev_b32_e32 v26, 2, v3
	v_mov_b32_e32 v31, s9
	v_cndmask_b32_e32 v3, v200, v204, vcc
	v_cmp_lt_i32_e32 vcc, v203, v2
	v_lshlrev_b32_e32 v27, 2, v3
	v_mov_b32_e32 v32, s13
	v_cndmask_b32_e32 v3, v200, v203, vcc
	v_cmp_lt_i32_e32 vcc, v202, v2
	v_lshlrev_b32_e32 v28, 2, v3
	v_mov_b32_e32 v3, 0
	v_cndmask_b32_e32 v2, v200, v202, vcc
	v_lshlrev_b32_e32 v29, 2, v2
	v_lshlrev_b32_e32 v2, 5, v47
	v_mov_b32_e32 v47, v3
	v_lshl_add_u64 v[4:5], s[14:15], 0, v[2:3]
	v_lshl_add_u64 v[6:7], s[10:11], 0, v[46:47]
	s_mov_b64 s[10:11], 0
	v_mov_b32_e32 v33, s8
	v_mov_b32_e32 v34, s12
	s_movk_i32 s18, 0x2000
	s_movk_i32 s19, 0x3000
	s_mov_b64 s[8:9], 0x800
	s_mov_b32 s24, 0x11000
	s_mov_b32 s25, 0x12000
	s_mov_b32 s26, 0x13000
	s_movk_i32 s27, 0xfff
	s_movk_i32 s28, 0x7fff
	s_mov_b32 s29, 0x800000
	s_mov_b32 s30, 0x801000
	s_mov_b32 s31, 0x802000
	s_mov_b32 s34, 0x803000
	s_mov_b32 s35, 0x804000
	v_mov_b32_e32 v35, 0x2d00000
	v_mov_b32_e32 v36, 0x1c00000
	s_branch .LBB0_44

.LBB0_51:
	s_or_b64 exec, exec, s[16:17]
	s_mov_b64 s[0:1], 0x1f000
	s_cmp_eq_u32 s98, 1
	s_cselect_b32 s0, 0, s0
	v_cmp_gt_u64_e32 vcc, s[0:1], v[44:45]
	s_and_saveexec_b64 s[4:5], vcc
	s_cbranch_execz .LBB0_54
	s_ashr_i32 s53, s52, 31
	s_mov_b32 s10, 0xffff0800
	v_mov_b32_e32 v3, 0
	s_lshl_b64 s[6:7], s[52:53], 9
	s_mov_b64 s[8:9], 0
	s_mov_b32 s11, -1
	s_mov_b64 s[12:13], 0xf800
	v_mov_b32_e32 v4, 0x2d00000
	v_mov_b32_e32 v5, 0x1c00000
	v_mov_b32_e32 v6, v3
	v_mov_b32_e32 v7, v3
	v_mov_b32_e32 v8, v3
	v_mov_b32_e32 v9, v3
	s_mov_b64 s[14:15], 0x1efff

.LBB0_54:
	s_or_b64 exec, exec, s[4:5]
	s_cmp_eq_u32 s98, 1
	s_cbranch_scc0 .Lp0_first
	s_mov_b32 s98, 0
	s_lshl_b32 s33, s52, 3
	s_ashr_i32 s53, s52, 31
	s_mov_b32 s3, 0
	s_branch .Lp3_resume
.Lp0_first:
	s_cmp_lt_i32 s52, 0x10000
	s_cbranch_scc1 .LBB0_66
	v_lshrrev_b32_e32 v2, 20, v0
	v_lshrrev_b32_e32 v0, 10, v0
	v_or_b32_e32 v0, v0, v2
	s_movk_i32 s0, 0x3ff
	v_and_or_b32 v0, v0, s0, v1
	v_cmp_eq_u32_e32 vcc, 0, v0
	s_waitcnt lgkmcnt(0)
	s_barrier
	s_and_saveexec_b64 s[4:5], vcc
	s_cbranch_execz .LBB0_65
	buffer_wbl2 sc1
	s_waitcnt vmcnt(0)
	s_load_dwordx2 s[6:7], s[20:21], 0x58
	v_mov_b32_e32 v2, 0
	s_mov_b64 s[8:9], exec
	v_mbcnt_lo_u32_b32 v1, s8, 0
	v_mbcnt_hi_u32_b32 v1, s9, v1
	s_waitcnt lgkmcnt(0)
	global_load_dword v0, v2, s[6:7] offset:40
	v_cmp_eq_u32_e32 vcc, 0, v1
	s_and_saveexec_b64 s[10:11], vcc
	s_cbranch_execz .LBB0_58
	s_bcnt1_i32_b64 s0, s[8:9]
	v_mov_b32_e32 v3, s0
	global_atomic_add v3, v2, v3, s[6:7] offset:32 sc0

.LBB0_354:
	s_cmp_lt_u32 s2, 16
	s_cbranch_scc1 .Lp3_resume
	s_mov_b32 s98, 1
	s_branch .Lp0_entry
